# GEMM k-loops rotated (next tile prelude+DMA issued under last MFMA group), OUT k-loop and DOWN tail loop reads pipelined with counted lgkmcnt
# speedup vs baseline: 1.0373x; 1.0148x over previous
; #define MFMA(a, b, c) __builtin_amdgcn_mfma_f32_32x32x16_bf16((a), (b), (c), 0, 0, 0)
;     ...
;     auto compute2 = [&](int buf) {
;       const char* lb = L0 + buf * BUFB;
; #pragma unroll
;       for (int ks = 0; ks < 4; ++ks) {
;         const int c = ks * 2 + hh;
;         bf16x8 wf[2], xf[MI];
; #pragma unroll
;         for (int j = 0; j < 2; ++j) { const int r = wn * 64 + j * 32 + l32; wf[j] = *(const bf16x8*)(lb + 256 * 128 + r * 128 + ((c ^ ((r >> 1) & 7)) << 4)); }
; #pragma unroll
;         for (int i = 0; i < MI; ++i) { const int r = wm * (MI * 32) + i * 32 + l32; xf[i] = *(const bf16x8*)(lb + r * 128 + ((c ^ ((r >> 1) & 7)) << 4)); }
; #pragma unroll
;         for (int i = 0; i < MI; ++i) {
;           acc[i][0] = MFMA(wf[0], xf[i], acc[i][0]);
;           acc[i][1] = MFMA(wf[1], xf[i], acc[i][1]);
;         }
;       }
;     };
;     ...
;       for (int kt = 0; kt < nk; ++kt) {
;         const int buf = kt & 1;
;         if (kt + 1 < nk) issue(kt + 1, buf ^ 1);
;         else if (chain & 2) issue_at(nmt * 256, nnt * BN, 0, buf ^ 1);
;         compute2(buf);
;         asm volatile("s_waitcnt vmcnt(0)" ::: "memory");
;         __syncthreads();
;       }
.LBB0_41:
	s_add_i32 s14, s58, 0
	v_add_u32_e32 v152, s14, v202
	v_add_u32_e32 v153, v152, v203
	v_add_u32_e32 v152, v152, v0
	ds_read_b128 v[148:151], v153 offset:32768
	ds_read_b128 v[212:215], v153 offset:36864
	ds_read_b128 v[204:207], v152
	ds_read_b128 v[216:219], v152 offset:4096
	ds_read_b128 v[220:223], v152 offset:8192
	ds_read_b128 v[224:227], v152 offset:12288
	v_add_u32_e32 v152, s14, v208
	v_add_u32_e32 v153, v152, v203
	v_add_u32_e32 v152, v152, v0
	s_waitcnt lgkmcnt(3)
	v_mfma_f32_32x32x16_bf16 v[114:129], v[148:151], v[204:207], v[114:129]
	s_add_u32 s10, s10, 0x80
	s_addc_u32 s11, s11, 0
	s_add_i32 s57, s57, 0x10000
	s_add_i32 s56, s56, 1
	s_cmpk_eq_i32 s10, 0x480
	ds_read_b128 v[228:231], v153 offset:32768
	v_mfma_f32_32x32x16_bf16 v[98:113], v[212:215], v[204:207], v[98:113]
	ds_read_b128 v[232:235], v153 offset:36864
	s_waitcnt lgkmcnt(4)
	v_mfma_f32_32x32x16_bf16 v[82:97], v[148:151], v[216:219], v[82:97]
	ds_read_b128 v[240:243], v152
	v_mfma_f32_32x32x16_bf16 v[66:81], v[212:215], v[216:219], v[66:81]
	ds_read_b128 v[216:219], v152 offset:4096
	s_waitcnt lgkmcnt(5)
	v_mfma_f32_32x32x16_bf16 v[50:65], v[148:151], v[220:223], v[50:65]
	v_mfma_f32_32x32x16_bf16 v[34:49], v[212:215], v[220:223], v[34:49]
	ds_read_b128 v[220:223], v152 offset:8192
	s_waitcnt lgkmcnt(5)
	v_mfma_f32_32x32x16_bf16 v[18:33], v[148:151], v[224:227], v[18:33]
	v_mfma_f32_32x32x16_bf16 v[2:17], v[212:215], v[224:227], v[2:17]
	ds_read_b128 v[224:227], v152 offset:12288
	v_add_u32_e32 v152, s14, v209
	v_add_u32_e32 v153, v152, v203
	v_add_u32_e32 v152, v152, v0
	s_waitcnt lgkmcnt(3)
	v_mfma_f32_32x32x16_bf16 v[114:129], v[228:231], v[240:243], v[114:129]
	ds_read_b128 v[148:151], v153 offset:32768
	v_mfma_f32_32x32x16_bf16 v[98:113], v[232:235], v[240:243], v[98:113]
	ds_read_b128 v[212:215], v153 offset:36864
	s_waitcnt lgkmcnt(4)
	v_mfma_f32_32x32x16_bf16 v[82:97], v[228:231], v[216:219], v[82:97]
	ds_read_b128 v[204:207], v152
	v_mfma_f32_32x32x16_bf16 v[66:81], v[232:235], v[216:219], v[66:81]
	ds_read_b128 v[216:219], v152 offset:4096
	s_waitcnt lgkmcnt(5)
	v_mfma_f32_32x32x16_bf16 v[50:65], v[228:231], v[220:223], v[50:65]
	v_mfma_f32_32x32x16_bf16 v[34:49], v[232:235], v[220:223], v[34:49]
	ds_read_b128 v[220:223], v152 offset:8192
	s_waitcnt lgkmcnt(5)
	v_mfma_f32_32x32x16_bf16 v[18:33], v[228:231], v[224:227], v[18:33]
	v_mfma_f32_32x32x16_bf16 v[2:17], v[232:235], v[224:227], v[2:17]
	ds_read_b128 v[224:227], v152 offset:12288
	v_add_u32_e32 v152, s14, v210
	v_add_u32_e32 v153, v152, v203
	v_add_u32_e32 v152, v152, v0
	s_waitcnt lgkmcnt(3)
	v_mfma_f32_32x32x16_bf16 v[114:129], v[148:151], v[204:207], v[114:129]
	ds_read_b128 v[228:231], v153 offset:32768
	v_mfma_f32_32x32x16_bf16 v[98:113], v[212:215], v[204:207], v[98:113]
	ds_read_b128 v[232:235], v153 offset:36864
	s_waitcnt lgkmcnt(4)
	v_mfma_f32_32x32x16_bf16 v[82:97], v[148:151], v[216:219], v[82:97]
	ds_read_b128 v[240:243], v152
	v_mfma_f32_32x32x16_bf16 v[66:81], v[212:215], v[216:219], v[66:81]
	ds_read_b128 v[216:219], v152 offset:4096
	s_waitcnt lgkmcnt(5)
	v_mfma_f32_32x32x16_bf16 v[50:65], v[148:151], v[220:223], v[50:65]
	v_mfma_f32_32x32x16_bf16 v[34:49], v[212:215], v[220:223], v[34:49]
	ds_read_b128 v[220:223], v152 offset:8192
	s_waitcnt lgkmcnt(5)
	v_mfma_f32_32x32x16_bf16 v[18:33], v[148:151], v[224:227], v[18:33]
	v_mfma_f32_32x32x16_bf16 v[2:17], v[212:215], v[224:227], v[2:17]
	ds_read_b128 v[224:227], v152 offset:12288
	s_waitcnt vmcnt(0)
	s_waitcnt vmcnt(0) lgkmcnt(0)
	s_barrier
	v_mfma_f32_32x32x16_bf16 v[114:129], v[228:231], v[240:243], v[114:129]
	v_mfma_f32_32x32x16_bf16 v[98:113], v[232:235], v[240:243], v[98:113]
	v_mfma_f32_32x32x16_bf16 v[82:97], v[228:231], v[216:219], v[82:97]
	v_mfma_f32_32x32x16_bf16 v[66:81], v[232:235], v[216:219], v[66:81]
	v_mfma_f32_32x32x16_bf16 v[50:65], v[228:231], v[220:223], v[50:65]
	v_mfma_f32_32x32x16_bf16 v[34:49], v[232:235], v[220:223], v[34:49]
	v_mfma_f32_32x32x16_bf16 v[18:33], v[228:231], v[224:227], v[18:33]
	v_mfma_f32_32x32x16_bf16 v[2:17], v[232:235], v[224:227], v[2:17]
	s_cbranch_scc1 .LBB0_49

; #define MFMA(a, b, c) __builtin_amdgcn_mfma_f32_32x32x16_bf16((a), (b), (c), 0, 0, 0)
;     ...
;     auto issue_at = [&](int mm0, int nn0, int kt, int buf) {
;       char* lb = L0 + buf * BUFB;
; #pragma unroll
;       for (int i = 0; i < 4; ++i) {
;         const int seg = wv * 4 + i, row = seg * 8 + gl_row;
;         const int c = (lane & 7) ^ ((row >> 1) & 7);
;         const u16* ap = (kt < g.split) ? g.a0 + (size_t)(mm0 + row) * g.ld0 + kt * g.ks0 : g.a1 + (size_t)(mm0 + row) * g.ld1 + (kt - g.split) * 64;
;         __builtin_amdgcn_global_load_lds((const unsigned*)(ap + c * 8), (__attribute__((address_space(3))) unsigned*)(lb + seg * 1024 + lane * 16), 16, 0, 0);
;       }
; #pragma unroll
;       for (int i = 0; i < BN / 64; ++i) {
;         const int seg = wv * (BN / 64) + i, row = seg * 8 + gl_row;
;         const int c = (lane & 7) ^ ((row >> 1) & 7);
;         __builtin_amdgcn_global_load_lds((const unsigned*)(g.W + (size_t)(nn0 + row) * g.K + kt * 64 + c * 8),
;                                          (__attribute__((address_space(3))) unsigned*)(lb + 256 * 128 + seg * 1024 + lane * 16), 16, 0, 0);
;       }
;     };
;     ...
;     auto compute2 = [&](int buf) {
;       const char* lb = L0 + buf * BUFB;
; #pragma unroll
;       for (int ks = 0; ks < 4; ++ks) {
;         const int c = ks * 2 + hh;
;         bf16x8 wf[2], xf[MI];
; #pragma unroll
;         for (int j = 0; j < 2; ++j) { const int r = wn * 64 + j * 32 + l32; wf[j] = *(const bf16x8*)(lb + 256 * 128 + r * 128 + ((c ^ ((r >> 1) & 7)) << 4)); }
; #pragma unroll
;         for (int i = 0; i < MI; ++i) { const int r = wm * (MI * 32) + i * 32 + l32; xf[i] = *(const bf16x8*)(lb + r * 128 + ((c ^ ((r >> 1) & 7)) << 4)); }
; #pragma unroll
;         for (int i = 0; i < MI; ++i) {
;           acc[i][0] = MFMA(wf[0], xf[i], acc[i][0]);
;           acc[i][1] = MFMA(wf[1], xf[i], acc[i][1]);
;         }
;       }
;     };
.Lgemm_rot_798:
	v_add_u32_e32 v0, s14, v174
	v_add_u32_e32 v176, v0, v171
	v_add_u32_e32 v0, v0, v170
	s_waitcnt lgkmcnt(3)
	v_mfma_f32_32x32x16_bf16 v[114:129], v[200:203], v[208:211], v[114:129]
	s_add_i32 s11, s11, 0x10000
	s_add_u32 s2, s2, 0x80
	s_addc_u32 s3, s3, 0
	s_cmpk_eq_i32 s2, 0x780
	ds_read_b128 v[224:227], v176 offset:32768
	v_mfma_f32_32x32x16_bf16 v[98:113], v[204:207], v[208:211], v[98:113]
	ds_read_b128 v[228:231], v176 offset:36864
	s_waitcnt lgkmcnt(4)
	v_mfma_f32_32x32x16_bf16 v[82:97], v[200:203], v[212:215], v[82:97]
	ds_read_b128 v[232:235], v0
	v_mfma_f32_32x32x16_bf16 v[66:81], v[204:207], v[212:215], v[66:81]
	ds_read_b128 v[240:243], v0 offset:4096
	s_waitcnt lgkmcnt(5)
	v_mfma_f32_32x32x16_bf16 v[50:65], v[200:203], v[216:219], v[50:65]
	ds_read_b128 v[244:247], v0 offset:8192
	v_mfma_f32_32x32x16_bf16 v[34:49], v[204:207], v[216:219], v[34:49]
	ds_read_b128 v[248:251], v0 offset:12288
	s_waitcnt lgkmcnt(6)
	v_mfma_f32_32x32x16_bf16 v[18:33], v[200:203], v[220:223], v[18:33]
	v_mfma_f32_32x32x16_bf16 v[2:17], v[204:207], v[220:223], v[2:17]
	v_add_u32_e32 v0, s14, v173
	v_add_u32_e32 v176, v0, v171
	v_add_u32_e32 v0, v0, v170
	s_waitcnt lgkmcnt(3)
	v_mfma_f32_32x32x16_bf16 v[114:129], v[224:227], v[232:235], v[114:129]
	ds_read_b128 v[200:203], v176 offset:32768
	v_mfma_f32_32x32x16_bf16 v[98:113], v[228:231], v[232:235], v[98:113]
	ds_read_b128 v[204:207], v176 offset:36864
	s_waitcnt lgkmcnt(4)
	v_mfma_f32_32x32x16_bf16 v[82:97], v[224:227], v[240:243], v[82:97]
	ds_read_b128 v[208:211], v0
	v_mfma_f32_32x32x16_bf16 v[66:81], v[228:231], v[240:243], v[66:81]
	ds_read_b128 v[212:215], v0 offset:4096
	s_waitcnt lgkmcnt(5)
	v_mfma_f32_32x32x16_bf16 v[50:65], v[224:227], v[244:247], v[50:65]
	ds_read_b128 v[216:219], v0 offset:8192
	v_mfma_f32_32x32x16_bf16 v[34:49], v[228:231], v[244:247], v[34:49]
	ds_read_b128 v[220:223], v0 offset:12288
	s_waitcnt lgkmcnt(6)
	v_mfma_f32_32x32x16_bf16 v[18:33], v[224:227], v[248:251], v[18:33]
	v_mfma_f32_32x32x16_bf16 v[2:17], v[228:231], v[248:251], v[2:17]
	v_add_u32_e32 v0, s14, v172
	v_add_u32_e32 v176, v0, v171
	v_add_u32_e32 v0, v0, v170
	s_waitcnt lgkmcnt(3)
	v_mfma_f32_32x32x16_bf16 v[114:129], v[200:203], v[208:211], v[114:129]
	ds_read_b128 v[224:227], v176 offset:32768
	v_mfma_f32_32x32x16_bf16 v[98:113], v[204:207], v[208:211], v[98:113]
	ds_read_b128 v[228:231], v176 offset:36864
	s_waitcnt lgkmcnt(4)
	v_mfma_f32_32x32x16_bf16 v[82:97], v[200:203], v[212:215], v[82:97]
	ds_read_b128 v[232:235], v0
	v_mfma_f32_32x32x16_bf16 v[66:81], v[204:207], v[212:215], v[66:81]
	ds_read_b128 v[240:243], v0 offset:4096
	s_waitcnt lgkmcnt(5)
	v_mfma_f32_32x32x16_bf16 v[50:65], v[200:203], v[216:219], v[50:65]
	ds_read_b128 v[244:247], v0 offset:8192
	v_mfma_f32_32x32x16_bf16 v[34:49], v[204:207], v[216:219], v[34:49]
	ds_read_b128 v[248:251], v0 offset:12288
	s_waitcnt lgkmcnt(6)
	v_mfma_f32_32x32x16_bf16 v[18:33], v[200:203], v[220:223], v[18:33]
	v_mfma_f32_32x32x16_bf16 v[2:17], v[204:207], v[220:223], v[2:17]
	s_waitcnt vmcnt(0)
	s_waitcnt vmcnt(0) lgkmcnt(0)
	s_barrier
	s_cbranch_scc1 .Lgemm_exit_798
	s_and_b32 s14, s11, 0x10000
	s_xor_b32 s15, s14, 0x10000
	s_add_i32 s15, s15, 0
	s_add_i32 s14, s14, 0
	v_add_u32_e32 v0, s14, v175
	v_add_u32_e32 v176, v0, v171
	v_add_u32_e32 v0, v0, v170
	ds_read_b128 v[200:203], v176 offset:32768
	ds_read_b128 v[204:207], v176 offset:36864
	ds_read_b128 v[208:211], v0
	ds_read_b128 v[212:215], v0 offset:4096
	ds_read_b128 v[216:219], v0 offset:8192
	ds_read_b128 v[220:223], v0 offset:12288
	v_mfma_f32_32x32x16_bf16 v[114:129], v[224:227], v[232:235], v[114:129]
	v_add3_u32 v0, s15, v168, v169
	v_add3_u32 v178, s15, v160, v169
	v_readfirstlane_b32 s16, v0
	v_lshl_add_u64 v[176:177], v[152:153], 0, s[2:3]
	s_mov_b32 m0, s16
	v_mfma_f32_32x32x16_bf16 v[98:113], v[228:231], v[232:235], v[98:113]
	v_readfirstlane_b32 s16, v178
	v_add3_u32 v199, s15, v162, v169
	global_load_lds_dwordx4 v[176:177], off
	v_lshl_add_u64 v[176:177], v[150:151], 0, s[2:3]
	s_mov_b32 m0, s16
	v_mfma_f32_32x32x16_bf16 v[82:97], v[224:227], v[240:243], v[82:97]
	v_readfirstlane_b32 s16, v199
	v_add3_u32 v254, s15, v166, v169
	global_load_lds_dwordx4 v[176:177], off
	v_lshl_add_u64 v[176:177], v[148:149], 0, s[2:3]
	s_mov_b32 m0, s16
	v_mfma_f32_32x32x16_bf16 v[66:81], v[228:231], v[240:243], v[66:81]
	v_readfirstlane_b32 s15, v254
	v_add_u32_e32 v0, 0x8000, v0
	global_load_lds_dwordx4 v[176:177], off
	v_lshl_add_u64 v[176:177], v[146:147], 0, s[2:3]
	s_mov_b32 m0, s15
	v_mfma_f32_32x32x16_bf16 v[50:65], v[224:227], v[244:247], v[50:65]
	v_readfirstlane_b32 s15, v0
	v_add_u32_e32 v0, 0x8000, v178
	global_load_lds_dwordx4 v[176:177], off
	v_lshl_add_u64 v[176:177], v[144:145], 0, s[2:3]
	s_mov_b32 m0, s15
	v_mfma_f32_32x32x16_bf16 v[34:49], v[228:231], v[244:247], v[34:49]
	v_readfirstlane_b32 s15, v0
	v_add_u32_e32 v0, 0x8000, v199
	global_load_lds_dwordx4 v[176:177], off
	v_lshl_add_u64 v[176:177], v[142:143], 0, s[2:3]
	s_mov_b32 m0, s15
	v_mfma_f32_32x32x16_bf16 v[18:33], v[224:227], v[248:251], v[18:33]
	v_readfirstlane_b32 s15, v0
	v_add_u32_e32 v0, 0x8000, v254
	global_load_lds_dwordx4 v[176:177], off
	v_lshl_add_u64 v[176:177], v[140:141], 0, s[2:3]
	s_mov_b32 m0, s15
	v_mfma_f32_32x32x16_bf16 v[2:17], v[228:231], v[248:251], v[2:17]
	v_readfirstlane_b32 s15, v0
	global_load_lds_dwordx4 v[176:177], off
	v_lshl_add_u64 v[176:177], v[138:139], 0, s[2:3]
	s_mov_b32 m0, s15
	global_load_lds_dwordx4 v[176:177], off
	s_branch .Lgemm_rot_798
;     ...
;     auto issue_at = [&](int mm0, int nn0, int kt, int buf) {
;       char* lb = L0 + buf * BUFB;
; #pragma unroll
;       for (int i = 0; i < 4; ++i) {
;         const int seg = wv * 4 + i, row = seg * 8 + gl_row;
;         const int c = (lane & 7) ^ ((row >> 1) & 7);
;         const u16* ap = (kt < g.split) ? g.a0 + (size_t)(mm0 + row) * g.ld0 + kt * g.ks0 : g.a1 + (size_t)(mm0 + row) * g.ld1 + (kt - g.split) * 64;
;         __builtin_amdgcn_global_load_lds((const unsigned*)(ap + c * 8), (__attribute__((address_space(3))) unsigned*)(lb + seg * 1024 + lane * 16), 16, 0, 0);
;       }
; #pragma unroll
;       for (int i = 0; i < BN / 64; ++i) {
;         const int seg = wv * (BN / 64) + i, row = seg * 8 + gl_row;
;         const int c = (lane & 7) ^ ((row >> 1) & 7);
;         __builtin_amdgcn_global_load_lds((const unsigned*)(g.W + (size_t)(nn0 + row) * g.K + kt * 64 + c * 8),
;                                          (__attribute__((address_space(3))) unsigned*)(lb + 256 * 128 + seg * 1024 + lane * 16), 16, 0, 0);
;       }
;     };
; template <int MODE, int EPI, int BN>
; DI void gemm_phase(CP p, const GArgs& g, int NT, char* smem) {
;     ...
;   for (int e = j; e < total; e += nj) {
;     const int grp = e / (8 * NT);
;     const int rem = e - grp * 8 * NT;
;     const int e2 = e + nj;
;     const bool has_next = can_chain && e2 < total;
;     const int grp2 = e2 / (8 * NT), rem2 = e2 - grp2 * 8 * NT;
;     const int chain = can_chain ? ((first ? 0 : 1) | (has_next ? 2 : 0)) : 0;
;     gemm_tile<MODE, EPI, BN>(p, g, x + 8 * (grp * 8 + (rem & 7)), rem >> 3, smem, chain, x + 8 * (grp2 * 8 + (rem2 & 7)), rem2 >> 3);
.Lgemm_exit_798:
	v_mfma_f32_32x32x16_bf16 v[114:129], v[224:227], v[232:235], v[114:129]
	v_mfma_f32_32x32x16_bf16 v[98:113], v[228:231], v[232:235], v[98:113]
	v_mfma_f32_32x32x16_bf16 v[82:97], v[224:227], v[240:243], v[82:97]
	v_mfma_f32_32x32x16_bf16 v[66:81], v[228:231], v[240:243], v[66:81]
	v_mfma_f32_32x32x16_bf16 v[50:65], v[224:227], v[244:247], v[50:65]
	v_mfma_f32_32x32x16_bf16 v[34:49], v[228:231], v[244:247], v[34:49]
	v_mfma_f32_32x32x16_bf16 v[18:33], v[224:227], v[248:251], v[18:33]
	v_mfma_f32_32x32x16_bf16 v[2:17], v[228:231], v[248:251], v[2:17]
	s_add_i32 s95, s95, s76
	s_cmpk_gt_u32 s95, 0x9f
	s_cselect_b64 s[92:93], -1, 0
	s_and_b64 vcc, exec, s[92:93]
	s_cbranch_vccnz .LBB0_801
	s_mul_hi_u32 s2, s95, 0xcccccccd
	s_lshr_b32 s3, s2, 6
	s_mulk_i32 s3, 0xffb0
	s_lshl_b32 s11, s95, 3
	s_add_i32 s3, s3, s95
	s_and_b32 s2, s2, 0xffffc0
	s_and_b32 s11, s11, 56
	s_or_b32 s2, s2, s11
	v_readlane_b32 s11, v252, 38
	s_lshl_b32 s3, s3, 5
	s_or_b32 s2, s2, s11
	s_and_b32 s3, s3, 0xffffff00
	s_lshl_b32 s2, s2, 8
	v_add_u32_e32 v148, s3, v161
	v_add_u32_e32 v138, s2, v157
	v_ashrrev_i32_e32 v149, 31, v148
	v_ashrrev_i32_e32 v139, 31, v138
	v_lshl_add_u64 v[176:177], s[68:69], 0, v[136:137]
	v_lshl_add_u64 v[136:137], s[70:71], 0, v[136:137]
	v_lshlrev_b64 v[148:149], 11, v[148:149]
	v_add3_u32 v0, 0, v168, v169
	v_add_u32_e32 v140, s2, v161
	v_add_u32_e32 v142, s2, v165
	v_add_u32_e32 v144, s2, v167
	v_lshlrev_b64 v[138:139], 11, v[138:139]
	v_lshl_add_u64 v[136:137], v[136:137], 0, v[148:149]
	v_lshl_add_u64 v[148:149], s[70:71], 0, v[134:135]
	v_lshl_add_u64 v[134:135], s[68:69], 0, v[134:135]
	v_readfirstlane_b32 s2, v0
	v_lshl_add_u64 v[134:135], v[134:135], 0, v[138:139]
	s_mov_b32 m0, s2
	v_ashrrev_i32_e32 v141, 31, v140
	global_load_lds_dwordx4 v[134:135], off
	v_add3_u32 v134, 0, v160, v169
	v_ashrrev_i32_e32 v143, 31, v142
	v_lshlrev_b64 v[140:141], 11, v[140:141]
	v_readfirstlane_b32 s2, v134
	v_add3_u32 v135, 0, v162, v169
	v_lshlrev_b64 v[142:143], 11, v[142:143]
	v_lshl_add_u64 v[202:203], s[70:71], 0, v[132:133]
	v_lshl_add_u64 v[132:133], s[68:69], 0, v[132:133]
	v_lshl_add_u64 v[140:141], v[176:177], 0, v[140:141]
	s_mov_b32 m0, s2
	v_readfirstlane_b32 s2, v135
	v_lshl_add_u64 v[132:133], v[132:133], 0, v[142:143]
	global_load_lds_dwordx4 v[140:141], off
	s_mov_b32 m0, s2
	v_ashrrev_i32_e32 v145, 31, v144
	v_add_u32_e32 v146, s3, v157
	global_load_lds_dwordx4 v[132:133], off
	v_add3_u32 v132, 0, v166, v169
	v_ashrrev_i32_e32 v147, 31, v146
	v_lshl_add_u64 v[200:201], s[68:69], 0, v[130:131]
	v_lshlrev_b64 v[144:145], 11, v[144:145]
	v_readfirstlane_b32 s2, v132
	v_add_u32_e32 v0, 0x8000, v0
	v_add_u32_e32 v150, s3, v165
	v_add_u32_e32 v152, s3, v167
	v_lshlrev_b64 v[146:147], 11, v[146:147]
	v_lshl_add_u64 v[144:145], v[200:201], 0, v[144:145]
	s_mov_b32 m0, s2
	v_readfirstlane_b32 s2, v0
	v_add_u32_e32 v0, 0x8000, v134
	v_ashrrev_i32_e32 v151, 31, v150
	v_ashrrev_i32_e32 v153, 31, v152
	v_lshl_add_u64 v[146:147], v[148:149], 0, v[146:147]
	global_load_lds_dwordx4 v[144:145], off
	s_mov_b32 m0, s2
	v_readfirstlane_b32 s2, v0
	v_add_u32_e32 v0, 0x8000, v135
	v_lshlrev_b64 v[150:151], 11, v[150:151]
	v_lshlrev_b64 v[152:153], 11, v[152:153]
	global_load_lds_dwordx4 v[146:147], off
	s_mov_b32 m0, s2
	v_readfirstlane_b32 s2, v0
	v_add_u32_e32 v0, 0x8000, v132
	v_lshl_add_u64 v[152:153], s[70:71], 0, v[152:153]
	v_lshl_add_u64 v[150:151], v[202:203], 0, v[150:151]
	global_load_lds_dwordx4 v[136:137], off
	s_mov_b32 m0, s2
	v_readfirstlane_b32 s2, v0
	global_load_lds_dwordx4 v[150:151], off
	v_lshl_add_u64 v[130:131], v[152:153], 0, v[130:131]
	s_mov_b32 m0, s2
	s_nop 0
	global_load_lds_dwordx4 v[130:131], off

; #define MFMA(a, b, c) __builtin_amdgcn_mfma_f32_32x32x16_bf16((a), (b), (c), 0, 0, 0)
;     ...
;     auto issue_at = [&](int mm0, int nn0, int kt, int buf) {
;       char* lb = L0 + buf * BUFB;
; #pragma unroll
;       for (int i = 0; i < 4; ++i) {
;         const int seg = wv * 4 + i, row = seg * 8 + gl_row;
;         const int c = (lane & 7) ^ ((row >> 1) & 7);
;         const u16* ap = (kt < g.split) ? g.a0 + (size_t)(mm0 + row) * g.ld0 + kt * g.ks0 : g.a1 + (size_t)(mm0 + row) * g.ld1 + (kt - g.split) * 64;
;         __builtin_amdgcn_global_load_lds((const unsigned*)(ap + c * 8), (__attribute__((address_space(3))) unsigned*)(lb + seg * 1024 + lane * 16), 16, 0, 0);
;       }
; #pragma unroll
;       for (int i = 0; i < BN / 64; ++i) {
;         const int seg = wv * (BN / 64) + i, row = seg * 8 + gl_row;
;         const int c = (lane & 7) ^ ((row >> 1) & 7);
;         __builtin_amdgcn_global_load_lds((const unsigned*)(g.W + (size_t)(nn0 + row) * g.K + kt * 64 + c * 8),
;                                          (__attribute__((address_space(3))) unsigned*)(lb + 256 * 128 + seg * 1024 + lane * 16), 16, 0, 0);
;       }
;     };
;     ...
;     auto compute2 = [&](int buf) {
;       const char* lb = L0 + buf * BUFB;
; #pragma unroll
;       for (int ks = 0; ks < 4; ++ks) {
;         const int c = ks * 2 + hh;
;         bf16x8 wf[2], xf[MI];
; #pragma unroll
;         for (int j = 0; j < 2; ++j) { const int r = wn * 64 + j * 32 + l32; wf[j] = *(const bf16x8*)(lb + 256 * 128 + r * 128 + ((c ^ ((r >> 1) & 7)) << 4)); }
; #pragma unroll
;         for (int i = 0; i < MI; ++i) { const int r = wm * (MI * 32) + i * 32 + l32; xf[i] = *(const bf16x8*)(lb + r * 128 + ((c ^ ((r >> 1) & 7)) << 4)); }
; #pragma unroll
;         for (int i = 0; i < MI; ++i) {
;           acc[i][0] = MFMA(wf[0], xf[i], acc[i][0]);
;           acc[i][1] = MFMA(wf[1], xf[i], acc[i][1]);
;         }
;       }
;     };
.LBB0_1274:
	s_and_b32 s59, s56, 0x10000
	s_xor_b32 s60, s59, 0x10000
	s_add_i32 s57, s58, 1
	s_add_i32 s60, s60, 0
	s_cmp_lt_u32 s58, 21
	s_cselect_b64 vcc, -1, 0
	v_add_u32_e32 v233, s59, v201
	v_add_u32_e32 v230, v233, v175
	v_add_u32_e32 v234, v233, v174
	ds_read_b128 v[202:205], v230 offset:32768
	ds_read_b128 v[206:209], v230 offset:36864
	ds_read_b128 v[210:213], v234
	ds_read_b128 v[214:217], v234 offset:4096
	ds_read_b128 v[218:221], v234 offset:8192
	ds_read_b128 v[222:225], v234 offset:12288
	v_lshl_add_u64 v[226:227], v[160:161], 0, s[2:3]
	v_lshl_add_u64 v[228:229], v[144:145], 0, s[2:3]
	v_add3_u32 v230, s60, v177, v178
	v_cndmask_b32_e32 v227, v229, v227, vcc
	v_cndmask_b32_e32 v226, v228, v226, vcc
	v_readfirstlane_b32 s58, v230
	v_lshl_add_u64 v[226:227], v[0:1], 1, v[226:227]
	s_mov_b32 m0, s58
	v_lshl_add_u64 v[228:229], v[142:143], 0, s[2:3]
	global_load_lds_dwordx4 v[226:227], off
	v_lshl_add_u64 v[226:227], v[158:159], 0, s[2:3]
	v_add3_u32 v231, s60, v169, v178
	v_cndmask_b32_e32 v227, v229, v227, vcc
	v_cndmask_b32_e32 v226, v228, v226, vcc
	v_readfirstlane_b32 s58, v231
	v_lshl_add_u64 v[226:227], v[130:131], 1, v[226:227]
	s_mov_b32 m0, s58
	v_lshl_add_u64 v[228:229], v[140:141], 0, s[2:3]
	global_load_lds_dwordx4 v[226:227], off
	v_lshl_add_u64 v[226:227], v[156:157], 0, s[2:3]
	v_add3_u32 v232, s60, v170, v178
	v_cndmask_b32_e32 v227, v229, v227, vcc
	v_cndmask_b32_e32 v226, v228, v226, vcc
	v_readfirstlane_b32 s58, v232
	v_lshl_add_u64 v[226:227], v[132:133], 1, v[226:227]
	s_mov_b32 m0, s58
	v_lshl_add_u64 v[228:229], v[138:139], 0, s[2:3]
	global_load_lds_dwordx4 v[226:227], off
	v_lshl_add_u64 v[226:227], v[154:155], 0, s[2:3]
	v_cndmask_b32_e32 v226, v228, v226, vcc
	v_add3_u32 v228, s60, v172, v178
	v_cndmask_b32_e32 v227, v229, v227, vcc
	v_readfirstlane_b32 s58, v228
	v_add_u32_e32 v229, 0x8000, v230
	v_lshl_add_u64 v[226:227], v[134:135], 1, v[226:227]
	s_mov_b32 m0, s58
	v_readfirstlane_b32 s58, v229
	v_add_u32_e32 v229, 0x8000, v231
	global_load_lds_dwordx4 v[226:227], off
	v_lshl_add_u64 v[226:227], v[146:147], 0, s[2:3]
	s_mov_b32 m0, s58
	v_readfirstlane_b32 s58, v229
	v_add_u32_e32 v229, 0x8000, v232
	global_load_lds_dwordx4 v[226:227], off
	v_lshl_add_u64 v[226:227], v[148:149], 0, s[2:3]
	s_mov_b32 m0, s58
	v_readfirstlane_b32 s58, v229
	v_add_u32_e32 v228, 0x8000, v228
	global_load_lds_dwordx4 v[226:227], off
	v_lshl_add_u64 v[226:227], v[150:151], 0, s[2:3]
	s_mov_b32 m0, s58
	v_readfirstlane_b32 s58, v228
	global_load_lds_dwordx4 v[226:227], off
	v_lshl_add_u64 v[226:227], v[152:153], 0, s[2:3]
	s_mov_b32 m0, s58
	s_add_i32 s58, s59, 0
	global_load_lds_dwordx4 v[226:227], off
.Lgemm_rot_1274:
	v_add_u32_e32 v233, s59, v200
	v_add_u32_e32 v230, v233, v175
	v_add_u32_e32 v234, v233, v174
	s_waitcnt lgkmcnt(3)
	v_mfma_f32_32x32x16_bf16 v[114:129], v[202:205], v[210:213], v[114:129]
	s_add_u32 s2, s2, 0x80
	s_addc_u32 s3, s3, 0
	s_add_i32 s56, s56, 0x10000
	s_cmpk_eq_i32 s2, 0x1580
	s_mov_b32 s58, s57
	ds_read_b128 v[240:243], v230 offset:32768
	v_mfma_f32_32x32x16_bf16 v[98:113], v[206:209], v[210:213], v[98:113]
	ds_read_b128 v[244:247], v230 offset:36864
	s_waitcnt lgkmcnt(4)
	v_mfma_f32_32x32x16_bf16 v[82:97], v[202:205], v[214:217], v[82:97]
	ds_read_b128 v[248:251], v234
	v_mfma_f32_32x32x16_bf16 v[66:81], v[206:209], v[214:217], v[66:81]
	ds_read_b128 v[214:217], v234 offset:4096
	s_waitcnt lgkmcnt(5)
	v_mfma_f32_32x32x16_bf16 v[50:65], v[202:205], v[218:221], v[50:65]
	v_mfma_f32_32x32x16_bf16 v[34:49], v[206:209], v[218:221], v[34:49]
	ds_read_b128 v[218:221], v234 offset:8192
	s_waitcnt lgkmcnt(5)
	v_mfma_f32_32x32x16_bf16 v[18:33], v[202:205], v[222:225], v[18:33]
	v_mfma_f32_32x32x16_bf16 v[2:17], v[206:209], v[222:225], v[2:17]
	ds_read_b128 v[222:225], v234 offset:12288
	v_add_u32_e32 v233, s59, v199
	v_add_u32_e32 v230, v233, v175
	v_add_u32_e32 v234, v233, v174
	s_waitcnt lgkmcnt(3)
	v_mfma_f32_32x32x16_bf16 v[114:129], v[240:243], v[248:251], v[114:129]
	ds_read_b128 v[202:205], v230 offset:32768
	v_mfma_f32_32x32x16_bf16 v[98:113], v[244:247], v[248:251], v[98:113]
	ds_read_b128 v[206:209], v230 offset:36864
	s_waitcnt lgkmcnt(4)
	v_mfma_f32_32x32x16_bf16 v[82:97], v[240:243], v[214:217], v[82:97]
	ds_read_b128 v[210:213], v234
	v_mfma_f32_32x32x16_bf16 v[66:81], v[244:247], v[214:217], v[66:81]
	ds_read_b128 v[214:217], v234 offset:4096
	s_waitcnt lgkmcnt(5)
	v_mfma_f32_32x32x16_bf16 v[50:65], v[240:243], v[218:221], v[50:65]
	v_mfma_f32_32x32x16_bf16 v[34:49], v[244:247], v[218:221], v[34:49]
	ds_read_b128 v[218:221], v234 offset:8192
	s_waitcnt lgkmcnt(5)
	v_mfma_f32_32x32x16_bf16 v[18:33], v[240:243], v[222:225], v[18:33]
	v_mfma_f32_32x32x16_bf16 v[2:17], v[244:247], v[222:225], v[2:17]
	ds_read_b128 v[222:225], v234 offset:12288
	v_add_u32_e32 v233, s59, v176
	v_add_u32_e32 v230, v233, v175
	v_add_u32_e32 v234, v233, v174
	s_waitcnt lgkmcnt(3)
	v_mfma_f32_32x32x16_bf16 v[114:129], v[202:205], v[210:213], v[114:129]
	ds_read_b128 v[240:243], v230 offset:32768
	v_mfma_f32_32x32x16_bf16 v[98:113], v[206:209], v[210:213], v[98:113]
	ds_read_b128 v[244:247], v230 offset:36864
	s_waitcnt lgkmcnt(4)
	v_mfma_f32_32x32x16_bf16 v[82:97], v[202:205], v[214:217], v[82:97]
	ds_read_b128 v[248:251], v234
	v_mfma_f32_32x32x16_bf16 v[66:81], v[206:209], v[214:217], v[66:81]
	ds_read_b128 v[214:217], v234 offset:4096
	s_waitcnt lgkmcnt(5)
	v_mfma_f32_32x32x16_bf16 v[50:65], v[202:205], v[218:221], v[50:65]
	v_mfma_f32_32x32x16_bf16 v[34:49], v[206:209], v[218:221], v[34:49]
	ds_read_b128 v[218:221], v234 offset:8192
	s_waitcnt lgkmcnt(5)
	v_mfma_f32_32x32x16_bf16 v[18:33], v[202:205], v[222:225], v[18:33]
	v_mfma_f32_32x32x16_bf16 v[2:17], v[206:209], v[222:225], v[2:17]
	ds_read_b128 v[222:225], v234 offset:12288
	s_waitcnt vmcnt(0)
	s_waitcnt vmcnt(0) lgkmcnt(0)
	s_barrier
;     ...
;     auto issue_at = [&](int mm0, int nn0, int kt, int buf) {
;       char* lb = L0 + buf * BUFB;
; #pragma unroll
;       for (int i = 0; i < 4; ++i) {
;         const int seg = wv * 4 + i, row = seg * 8 + gl_row;
;         const int c = (lane & 7) ^ ((row >> 1) & 7);
;         const u16* ap = (kt < g.split) ? g.a0 + (size_t)(mm0 + row) * g.ld0 + kt * g.ks0 : g.a1 + (size_t)(mm0 + row) * g.ld1 + (kt - g.split) * 64;
;         __builtin_amdgcn_global_load_lds((const unsigned*)(ap + c * 8), (__attribute__((address_space(3))) unsigned*)(lb + seg * 1024 + lane * 16), 16, 0, 0);
;       }
; #pragma unroll
;       for (int i = 0; i < BN / 64; ++i) {
;         const int seg = wv * (BN / 64) + i, row = seg * 8 + gl_row;
;         const int c = (lane & 7) ^ ((row >> 1) & 7);
;         __builtin_amdgcn_global_load_lds((const unsigned*)(g.W + (size_t)(nn0 + row) * g.K + kt * 64 + c * 8),
;                                          (__attribute__((address_space(3))) unsigned*)(lb + 256 * 128 + seg * 1024 + lane * 16), 16, 0, 0);
;       }
;     };
; template <int MODE, int EPI, int BN>
; DI void gemm_phase(CP p, const GArgs& g, int NT, char* smem) {
;     ...
;   for (int e = j; e < total; e += nj) {
;     const int grp = e / (8 * NT);
;     const int rem = e - grp * 8 * NT;
;     const int e2 = e + nj;
;     const bool has_next = can_chain && e2 < total;
;     const int grp2 = e2 / (8 * NT), rem2 = e2 - grp2 * 8 * NT;
;     const int chain = can_chain ? ((first ? 0 : 1) | (has_next ? 2 : 0)) : 0;
;     gemm_tile<MODE, EPI, BN>(p, g, x + 8 * (grp * 8 + (rem & 7)), rem >> 3, smem, chain, x + 8 * (grp2 * 8 + (rem2 & 7)), rem2 >> 3);
	s_cbranch_scc1 .Lgemm_exit_1274
	s_and_b32 s59, s56, 0x10000
	s_xor_b32 s60, s59, 0x10000
	s_add_i32 s57, s58, 1
	s_add_i32 s60, s60, 0
	s_cmp_lt_u32 s58, 21
	s_cselect_b64 vcc, -1, 0
	v_add_u32_e32 v233, s59, v201
	v_add_u32_e32 v230, v233, v175
	v_add_u32_e32 v234, v233, v174
	ds_read_b128 v[202:205], v230 offset:32768
	ds_read_b128 v[206:209], v230 offset:36864
	ds_read_b128 v[210:213], v234
	v_mfma_f32_32x32x16_bf16 v[114:129], v[240:243], v[248:251], v[114:129]
	v_lshl_add_u64 v[226:227], v[160:161], 0, s[2:3]
	v_lshl_add_u64 v[228:229], v[144:145], 0, s[2:3]
	v_add3_u32 v230, s60, v177, v178
	v_cndmask_b32_e32 v227, v229, v227, vcc
	v_cndmask_b32_e32 v226, v228, v226, vcc
	v_readfirstlane_b32 s58, v230
	v_lshl_add_u64 v[226:227], v[0:1], 1, v[226:227]
	s_mov_b32 m0, s58
	v_mfma_f32_32x32x16_bf16 v[98:113], v[244:247], v[248:251], v[98:113]
	v_lshl_add_u64 v[228:229], v[142:143], 0, s[2:3]
	global_load_lds_dwordx4 v[226:227], off
	v_lshl_add_u64 v[226:227], v[158:159], 0, s[2:3]
	v_add3_u32 v231, s60, v169, v178
	v_cndmask_b32_e32 v227, v229, v227, vcc
	v_cndmask_b32_e32 v226, v228, v226, vcc
	v_readfirstlane_b32 s58, v231
	v_lshl_add_u64 v[226:227], v[130:131], 1, v[226:227]
	v_mfma_f32_32x32x16_bf16 v[82:97], v[240:243], v[214:217], v[82:97]
	s_mov_b32 m0, s58
	v_lshl_add_u64 v[228:229], v[140:141], 0, s[2:3]
	global_load_lds_dwordx4 v[226:227], off
	v_lshl_add_u64 v[226:227], v[156:157], 0, s[2:3]
	v_add3_u32 v232, s60, v170, v178
	v_cndmask_b32_e32 v227, v229, v227, vcc
	v_cndmask_b32_e32 v226, v228, v226, vcc
	v_readfirstlane_b32 s58, v232
	v_mfma_f32_32x32x16_bf16 v[66:81], v[244:247], v[214:217], v[66:81]
	ds_read_b128 v[214:217], v234 offset:4096
	v_lshl_add_u64 v[226:227], v[132:133], 1, v[226:227]
	s_mov_b32 m0, s58
	v_lshl_add_u64 v[228:229], v[138:139], 0, s[2:3]
	global_load_lds_dwordx4 v[226:227], off
	v_lshl_add_u64 v[226:227], v[154:155], 0, s[2:3]
	v_cndmask_b32_e32 v226, v228, v226, vcc
	v_add3_u32 v228, s60, v172, v178
	v_cndmask_b32_e32 v227, v229, v227, vcc
	v_mfma_f32_32x32x16_bf16 v[50:65], v[240:243], v[218:221], v[50:65]
	v_readfirstlane_b32 s58, v228
	v_add_u32_e32 v229, 0x8000, v230
	v_lshl_add_u64 v[226:227], v[134:135], 1, v[226:227]
	s_mov_b32 m0, s58
	v_readfirstlane_b32 s58, v229
	v_add_u32_e32 v229, 0x8000, v231
	global_load_lds_dwordx4 v[226:227], off
	v_lshl_add_u64 v[226:227], v[146:147], 0, s[2:3]
	v_mfma_f32_32x32x16_bf16 v[34:49], v[244:247], v[218:221], v[34:49]
	ds_read_b128 v[218:221], v234 offset:8192
	s_mov_b32 m0, s58
	v_readfirstlane_b32 s58, v229
	v_add_u32_e32 v229, 0x8000, v232
	global_load_lds_dwordx4 v[226:227], off
	v_lshl_add_u64 v[226:227], v[148:149], 0, s[2:3]
	s_mov_b32 m0, s58
	v_readfirstlane_b32 s58, v229
	v_add_u32_e32 v228, 0x8000, v228
	v_mfma_f32_32x32x16_bf16 v[18:33], v[240:243], v[222:225], v[18:33]
	global_load_lds_dwordx4 v[226:227], off
	v_lshl_add_u64 v[226:227], v[150:151], 0, s[2:3]
	s_mov_b32 m0, s58
	v_readfirstlane_b32 s58, v228
	global_load_lds_dwordx4 v[226:227], off
	v_lshl_add_u64 v[226:227], v[152:153], 0, s[2:3]
	s_mov_b32 m0, s58
	s_add_i32 s58, s59, 0
	v_mfma_f32_32x32x16_bf16 v[2:17], v[244:247], v[222:225], v[2:17]
	ds_read_b128 v[222:225], v234 offset:12288
	global_load_lds_dwordx4 v[226:227], off
	s_branch .Lgemm_rot_1274
.Lgemm_exit_1274:
	v_mfma_f32_32x32x16_bf16 v[114:129], v[240:243], v[248:251], v[114:129]
	v_mfma_f32_32x32x16_bf16 v[98:113], v[244:247], v[248:251], v[98:113]
	v_mfma_f32_32x32x16_bf16 v[82:97], v[240:243], v[214:217], v[82:97]
	v_mfma_f32_32x32x16_bf16 v[66:81], v[244:247], v[214:217], v[66:81]
	v_mfma_f32_32x32x16_bf16 v[50:65], v[240:243], v[218:221], v[50:65]
	v_mfma_f32_32x32x16_bf16 v[34:49], v[244:247], v[218:221], v[34:49]
	v_mfma_f32_32x32x16_bf16 v[18:33], v[240:243], v[222:225], v[18:33]
	v_mfma_f32_32x32x16_bf16 v[2:17], v[244:247], v[222:225], v[2:17]
	s_add_i32 s15, s15, s10
	s_cmp_gt_u32 s15, 63
	s_cselect_b64 s[58:59], -1, 0
	s_and_b64 vcc, exec, s[58:59]
	s_cbranch_vccnz .LBB0_1277
	s_lshr_b32 s2, s15, 2
	s_and_b32 s2, s2, 0xffffff8
	s_and_b32 s3, s15, 7
	s_or_b32 s3, s2, s3
	s_lshl_b32 s2, s2, 7
	s_lshl_b32 s56, s15, 5
	s_sub_i32 s2, s56, s2
	s_lshl_b32 s3, s3, 11
	s_and_b32 s2, s2, 0xffffff00
	s_or_b32 s3, s3, s71
	v_add_u32_e32 v144, s2, v173
	v_lshlrev_b64 v[130:131], 1, v[130:131]
	v_mov_b64_e32 v[142:143], s[46:47]
	v_lshlrev_b64 v[132:133], 1, v[132:133]
	v_add_u32_e32 v0, s3, v163
	v_add_u32_e32 v148, s3, v168
	v_add_u32_e32 v149, s3, v171
	v_add_u32_e32 v150, s3, v173
	v_add_u32_e32 v151, s2, v163
	v_add_u32_e32 v146, s2, v168
	v_add_u32_e32 v147, s2, v171
	v_lshl_add_u64 v[138:139], s[42:43], 0, v[130:131]
	v_lshlrev_b64 v[134:135], 1, v[134:135]
	v_lshl_add_u64 v[130:131], s[46:47], 0, v[130:131]
	v_mad_i64_i32 v[142:143], s[2:3], v144, s96, v[142:143]
	v_lshl_add_u64 v[144:145], s[46:47], 0, v[132:133]
	v_lshl_add_u64 v[140:141], s[42:43], 0, v[134:135]
	v_mad_i64_i32 v[144:145], s[2:3], v147, s96, v[144:145]
	v_mad_i64_i32 v[130:131], s[2:3], v146, s96, v[130:131]
	v_lshl_add_u64 v[146:147], s[46:47], 0, v[136:137]
	v_lshl_add_u64 v[132:133], s[42:43], 0, v[132:133]
	v_lshl_add_u64 v[136:137], s[42:43], 0, v[136:137]
	v_mad_i64_i32 v[146:147], s[2:3], v151, s96, v[146:147]
	v_mad_i64_i32 v[140:141], s[2:3], v150, s29, v[140:141]
	v_mad_i64_i32 v[132:133], s[2:3], v149, s29, v[132:133]
	v_mad_i64_i32 v[138:139], s[2:3], v148, s29, v[138:139]
	v_mad_i64_i32 v[136:137], s[2:3], v0, s29, v[136:137]
	v_add3_u32 v0, 0, v177, v178
	s_nop 0
	v_readfirstlane_b32 s2, v0
	s_mov_b32 m0, s2
	v_add_u32_e32 v0, 0x8000, v0
	global_load_lds_dwordx4 v[136:137], off
	v_add3_u32 v136, 0, v169, v178
	v_add3_u32 v137, 0, v170, v178
	v_readfirstlane_b32 s2, v136
	s_mov_b32 m0, s2
	v_readfirstlane_b32 s2, v137
	global_load_lds_dwordx4 v[138:139], off
	s_mov_b32 m0, s2
	s_nop 0
	global_load_lds_dwordx4 v[132:133], off
	v_add3_u32 v132, 0, v172, v178
	s_nop 0
	v_readfirstlane_b32 s2, v132
	s_mov_b32 m0, s2
	v_readfirstlane_b32 s2, v0
	v_add_u32_e32 v0, 0x8000, v136
	global_load_lds_dwordx4 v[140:141], off
	s_mov_b32 m0, s2
	v_readfirstlane_b32 s2, v0
	v_add_u32_e32 v0, 0x8000, v137
	global_load_lds_dwordx4 v[146:147], off
	s_mov_b32 m0, s2
	v_readfirstlane_b32 s2, v0
	v_add_u32_e32 v0, 0x8000, v132
	global_load_lds_dwordx4 v[130:131], off
	s_mov_b32 m0, s2
	v_readfirstlane_b32 s2, v0
	global_load_lds_dwordx4 v[144:145], off
	v_lshl_add_u64 v[130:131], v[142:143], 0, v[134:135]
	s_mov_b32 m0, s2
	s_nop 0
	global_load_lds_dwordx4 v[130:131], off

; #define MFMA(a, b, c) __builtin_amdgcn_mfma_f32_32x32x16_bf16((a), (b), (c), 0, 0, 0)
;     ...
;     auto compute2 = [&](int buf) {
;       const char* lb = L0 + buf * BUFB;
; #pragma unroll
;       for (int ks = 0; ks < 4; ++ks) {
;         const int c = ks * 2 + hh;
;         bf16x8 wf[2], xf[MI];
; #pragma unroll
;         for (int j = 0; j < 2; ++j) { const int r = wn * 64 + j * 32 + l32; wf[j] = *(const bf16x8*)(lb + 256 * 128 + r * 128 + ((c ^ ((r >> 1) & 7)) << 4)); }
; #pragma unroll
;         for (int i = 0; i < MI; ++i) { const int r = wm * (MI * 32) + i * 32 + l32; xf[i] = *(const bf16x8*)(lb + r * 128 + ((c ^ ((r >> 1) & 7)) << 4)); }
; #pragma unroll
;         for (int i = 0; i < MI; ++i) {
;           acc[i][0] = MFMA(wf[0], xf[i], acc[i][0]);
;           acc[i][1] = MFMA(wf[1], xf[i], acc[i][1]);
;         }
;       }
;     };
.LBB0_1294:
	s_add_i32 s52, s59, 0
	v_add_u32_e32 v53, s52, v69
	v_add_u32_e32 v55, v53, v68
	ds_read_b128 v[82:85], v55 offset:32768
	v_add_u32_e32 v57, v53, v62
	v_add_u32_e32 v73, v57, v68
	ds_read_b128 v[86:89], v73
	v_add_u32_e32 v73, v57, v70
	s_mov_b64 s[52:53], -1
	s_and_b64 vcc, exec, s[50:51]
	ds_read_b128 v[90:93], v55 offset:36864
	v_add_u32_e32 v55, v53, v70
	ds_read_b128 v[94:97], v55 offset:32768
	ds_read_b128 v[98:101], v73
	v_add_u32_e32 v73, v57, v71
	ds_read_b128 v[102:105], v55 offset:36864
	v_add_u32_e32 v55, v53, v71
	v_add_u32_e32 v53, v53, v72
	ds_read_b128 v[106:109], v55 offset:32768
	ds_read_b128 v[110:113], v73
	ds_read_b128 v[114:117], v55 offset:36864
	v_add_u32_e32 v55, v57, v72
	ds_read_b128 v[118:121], v53 offset:32768
	ds_read_b128 v[122:125], v55
	ds_read_b128 v[126:129], v53 offset:36864
	s_waitcnt lgkmcnt(10)
	v_mfma_f32_32x32x16_bf16 v[18:33], v[82:85], v[86:89], v[18:33]
	s_waitcnt lgkmcnt(9)
	v_mfma_f32_32x32x16_bf16 v[2:17], v[90:93], v[86:89], v[2:17]
	s_waitcnt lgkmcnt(7)
	v_mfma_f32_32x32x16_bf16 v[18:33], v[94:97], v[98:101], v[18:33]
	s_waitcnt lgkmcnt(6)
	v_mfma_f32_32x32x16_bf16 v[2:17], v[102:105], v[98:101], v[2:17]
	s_waitcnt lgkmcnt(4)
	v_mfma_f32_32x32x16_bf16 v[18:33], v[106:109], v[110:113], v[18:33]
	s_waitcnt lgkmcnt(3)
	v_mfma_f32_32x32x16_bf16 v[2:17], v[114:117], v[110:113], v[2:17]
	s_waitcnt lgkmcnt(1)
	v_mfma_f32_32x32x16_bf16 v[18:33], v[118:121], v[122:125], v[18:33]
	s_waitcnt lgkmcnt(0)
	v_mfma_f32_32x32x16_bf16 v[2:17], v[126:129], v[122:125], v[2:17]
	s_cbranch_vccz .LBB0_1296
	s_waitcnt vmcnt(0)
	s_mov_b64 s[52:53], 0

; #define MFMA(a, b, c) __builtin_amdgcn_mfma_f32_32x32x16_bf16((a), (b), (c), 0, 0, 0)
;     ...
;     auto issue_at = [&](int mm0, int nn0, int kt, int buf) {
;       char* lb = L0 + buf * BUFB;
; #pragma unroll
;       for (int i = 0; i < 4; ++i) {
;         const int seg = wv * 4 + i, row = seg * 8 + gl_row;
;         const int c = (lane & 7) ^ ((row >> 1) & 7);
;         const u16* ap = (kt < g.split) ? g.a0 + (size_t)(mm0 + row) * g.ld0 + kt * g.ks0 : g.a1 + (size_t)(mm0 + row) * g.ld1 + (kt - g.split) * 64;
;         __builtin_amdgcn_global_load_lds((const unsigned*)(ap + c * 8), (__attribute__((address_space(3))) unsigned*)(lb + seg * 1024 + lane * 16), 16, 0, 0);
;       }
; #pragma unroll
;       for (int i = 0; i < BN / 64; ++i) {
;         const int seg = wv * (BN / 64) + i, row = seg * 8 + gl_row;
;         const int c = (lane & 7) ^ ((row >> 1) & 7);
;         __builtin_amdgcn_global_load_lds((const unsigned*)(g.W + (size_t)(nn0 + row) * g.K + kt * 64 + c * 8),
;                                          (__attribute__((address_space(3))) unsigned*)(lb + 256 * 128 + seg * 1024 + lane * 16), 16, 0, 0);
;       }
;     };
;     ...
;     auto compute2 = [&](int buf) {
;       const char* lb = L0 + buf * BUFB;
; #pragma unroll
;       for (int ks = 0; ks < 4; ++ks) {
;         const int c = ks * 2 + hh;
;         bf16x8 wf[2], xf[MI];
; #pragma unroll
;         for (int j = 0; j < 2; ++j) { const int r = wn * 64 + j * 32 + l32; wf[j] = *(const bf16x8*)(lb + 256 * 128 + r * 128 + ((c ^ ((r >> 1) & 7)) << 4)); }
; #pragma unroll
;         for (int i = 0; i < MI; ++i) { const int r = wm * (MI * 32) + i * 32 + l32; xf[i] = *(const bf16x8*)(lb + r * 128 + ((c ^ ((r >> 1) & 7)) << 4)); }
; #pragma unroll
;         for (int i = 0; i < MI; ++i) {
;           acc[i][0] = MFMA(wf[0], xf[i], acc[i][0]);
;           acc[i][1] = MFMA(wf[1], xf[i], acc[i][1]);
;         }
;       }
;     };
.Lgemm_rot_1371:
	v_add_u32_e32 v0, s17, v173
	v_add_u32_e32 v175, v0, v170
	v_add_u32_e32 v0, v0, v169
	s_waitcnt lgkmcnt(3)
	v_mfma_f32_32x32x16_bf16 v[114:129], v[200:203], v[208:211], v[114:129]
	s_add_i32 s16, s16, 0x10000
	s_add_u32 s10, s10, 0x80
	s_addc_u32 s11, s11, 0
	s_cmpk_eq_i32 s10, 0x780
	ds_read_b128 v[224:227], v175 offset:32768
	v_mfma_f32_32x32x16_bf16 v[98:113], v[204:207], v[208:211], v[98:113]
	ds_read_b128 v[228:231], v175 offset:36864
	s_waitcnt lgkmcnt(4)
	v_mfma_f32_32x32x16_bf16 v[82:97], v[200:203], v[212:215], v[82:97]
	ds_read_b128 v[232:235], v0
	v_mfma_f32_32x32x16_bf16 v[66:81], v[204:207], v[212:215], v[66:81]
	ds_read_b128 v[240:243], v0 offset:4096
	s_waitcnt lgkmcnt(5)
	v_mfma_f32_32x32x16_bf16 v[50:65], v[200:203], v[216:219], v[50:65]
	ds_read_b128 v[244:247], v0 offset:8192
	v_mfma_f32_32x32x16_bf16 v[34:49], v[204:207], v[216:219], v[34:49]
	ds_read_b128 v[248:251], v0 offset:12288
	s_waitcnt lgkmcnt(6)
	v_mfma_f32_32x32x16_bf16 v[18:33], v[200:203], v[220:223], v[18:33]
	v_mfma_f32_32x32x16_bf16 v[2:17], v[204:207], v[220:223], v[2:17]
	v_add_u32_e32 v0, s17, v172
	v_add_u32_e32 v175, v0, v170
	v_add_u32_e32 v0, v0, v169
	s_waitcnt lgkmcnt(3)
	v_mfma_f32_32x32x16_bf16 v[114:129], v[224:227], v[232:235], v[114:129]
	ds_read_b128 v[200:203], v175 offset:32768
	v_mfma_f32_32x32x16_bf16 v[98:113], v[228:231], v[232:235], v[98:113]
	ds_read_b128 v[204:207], v175 offset:36864
	s_waitcnt lgkmcnt(4)
	v_mfma_f32_32x32x16_bf16 v[82:97], v[224:227], v[240:243], v[82:97]
	ds_read_b128 v[208:211], v0
	v_mfma_f32_32x32x16_bf16 v[66:81], v[228:231], v[240:243], v[66:81]
	ds_read_b128 v[212:215], v0 offset:4096
	s_waitcnt lgkmcnt(5)
	v_mfma_f32_32x32x16_bf16 v[50:65], v[224:227], v[244:247], v[50:65]
	ds_read_b128 v[216:219], v0 offset:8192
	v_mfma_f32_32x32x16_bf16 v[34:49], v[228:231], v[244:247], v[34:49]
	ds_read_b128 v[220:223], v0 offset:12288
	s_waitcnt lgkmcnt(6)
	v_mfma_f32_32x32x16_bf16 v[18:33], v[224:227], v[248:251], v[18:33]
	v_mfma_f32_32x32x16_bf16 v[2:17], v[228:231], v[248:251], v[2:17]
	v_add_u32_e32 v0, s17, v171
	v_add_u32_e32 v175, v0, v170
	v_add_u32_e32 v0, v0, v169
	s_waitcnt lgkmcnt(3)
	v_mfma_f32_32x32x16_bf16 v[114:129], v[200:203], v[208:211], v[114:129]
	ds_read_b128 v[224:227], v175 offset:32768
	v_mfma_f32_32x32x16_bf16 v[98:113], v[204:207], v[208:211], v[98:113]
	ds_read_b128 v[228:231], v175 offset:36864
	s_waitcnt lgkmcnt(4)
	v_mfma_f32_32x32x16_bf16 v[82:97], v[200:203], v[212:215], v[82:97]
	ds_read_b128 v[232:235], v0
	v_mfma_f32_32x32x16_bf16 v[66:81], v[204:207], v[212:215], v[66:81]
	ds_read_b128 v[240:243], v0 offset:4096
	s_waitcnt lgkmcnt(5)
	v_mfma_f32_32x32x16_bf16 v[50:65], v[200:203], v[216:219], v[50:65]
	ds_read_b128 v[244:247], v0 offset:8192
	v_mfma_f32_32x32x16_bf16 v[34:49], v[204:207], v[216:219], v[34:49]
	ds_read_b128 v[248:251], v0 offset:12288
	s_waitcnt lgkmcnt(6)
	v_mfma_f32_32x32x16_bf16 v[18:33], v[200:203], v[220:223], v[18:33]
	v_mfma_f32_32x32x16_bf16 v[2:17], v[204:207], v[220:223], v[2:17]
	s_waitcnt vmcnt(0)
	s_waitcnt vmcnt(0) lgkmcnt(0)
	s_barrier
	s_cbranch_scc1 .Lgemm_exit_1371
	s_and_b32 s17, s16, 0x10000
	s_xor_b32 s43, s17, 0x10000
	s_add_i32 s43, s43, 0
	s_add_i32 s17, s17, 0
	v_add_u32_e32 v0, s17, v174
	v_add_u32_e32 v175, v0, v170
	v_add_u32_e32 v0, v0, v169
	ds_read_b128 v[200:203], v175 offset:32768
	ds_read_b128 v[204:207], v175 offset:36864
	ds_read_b128 v[208:211], v0
	ds_read_b128 v[212:215], v0 offset:4096
	ds_read_b128 v[216:219], v0 offset:8192
	ds_read_b128 v[220:223], v0 offset:12288
	v_mfma_f32_32x32x16_bf16 v[114:129], v[224:227], v[232:235], v[114:129]
	v_add3_u32 v0, s43, v167, v168
	v_add3_u32 v175, s43, v157, v168
	v_readfirstlane_b32 s45, v0
	v_lshl_add_u64 v[176:177], v[152:153], 0, s[10:11]
	s_mov_b32 m0, s45
	v_mfma_f32_32x32x16_bf16 v[98:113], v[228:231], v[232:235], v[98:113]
	v_readfirstlane_b32 s45, v175
	v_add3_u32 v178, s43, v159, v168
	global_load_lds_dwordx4 v[176:177], off
	v_lshl_add_u64 v[176:177], v[150:151], 0, s[10:11]
	s_mov_b32 m0, s45
	v_mfma_f32_32x32x16_bf16 v[82:97], v[224:227], v[240:243], v[82:97]
	v_readfirstlane_b32 s45, v178
	v_add3_u32 v199, s43, v165, v168
	global_load_lds_dwordx4 v[176:177], off
	v_lshl_add_u64 v[176:177], v[148:149], 0, s[10:11]
	s_mov_b32 m0, s45
	v_mfma_f32_32x32x16_bf16 v[66:81], v[228:231], v[240:243], v[66:81]
	v_readfirstlane_b32 s43, v199
	v_add_u32_e32 v0, 0x8000, v0
	global_load_lds_dwordx4 v[176:177], off
	v_lshl_add_u64 v[176:177], v[146:147], 0, s[10:11]
	s_mov_b32 m0, s43
	v_mfma_f32_32x32x16_bf16 v[50:65], v[224:227], v[244:247], v[50:65]
	v_readfirstlane_b32 s43, v0
	v_add_u32_e32 v0, 0x8000, v175
	global_load_lds_dwordx4 v[176:177], off
	v_lshl_add_u64 v[176:177], v[144:145], 0, s[10:11]
	s_mov_b32 m0, s43
	v_mfma_f32_32x32x16_bf16 v[34:49], v[228:231], v[244:247], v[34:49]
	v_readfirstlane_b32 s43, v0
	v_add_u32_e32 v0, 0x8000, v178
	global_load_lds_dwordx4 v[176:177], off
	v_lshl_add_u64 v[176:177], v[142:143], 0, s[10:11]
	s_mov_b32 m0, s43
	v_mfma_f32_32x32x16_bf16 v[18:33], v[224:227], v[248:251], v[18:33]
	v_readfirstlane_b32 s43, v0
	v_add_u32_e32 v0, 0x8000, v199
	global_load_lds_dwordx4 v[176:177], off
	v_lshl_add_u64 v[176:177], v[140:141], 0, s[10:11]
	s_mov_b32 m0, s43
	v_mfma_f32_32x32x16_bf16 v[2:17], v[228:231], v[248:251], v[2:17]
	v_readfirstlane_b32 s43, v0
	global_load_lds_dwordx4 v[176:177], off
	v_lshl_add_u64 v[176:177], v[138:139], 0, s[10:11]
	s_mov_b32 m0, s43
	global_load_lds_dwordx4 v[176:177], off
	s_branch .Lgemm_rot_1371
;     ...
;     auto issue_at = [&](int mm0, int nn0, int kt, int buf) {
;       char* lb = L0 + buf * BUFB;
; #pragma unroll
;       for (int i = 0; i < 4; ++i) {
;         const int seg = wv * 4 + i, row = seg * 8 + gl_row;
;         const int c = (lane & 7) ^ ((row >> 1) & 7);
;         const u16* ap = (kt < g.split) ? g.a0 + (size_t)(mm0 + row) * g.ld0 + kt * g.ks0 : g.a1 + (size_t)(mm0 + row) * g.ld1 + (kt - g.split) * 64;
;         __builtin_amdgcn_global_load_lds((const unsigned*)(ap + c * 8), (__attribute__((address_space(3))) unsigned*)(lb + seg * 1024 + lane * 16), 16, 0, 0);
;       }
; #pragma unroll
;       for (int i = 0; i < BN / 64; ++i) {
;         const int seg = wv * (BN / 64) + i, row = seg * 8 + gl_row;
;         const int c = (lane & 7) ^ ((row >> 1) & 7);
;         __builtin_amdgcn_global_load_lds((const unsigned*)(g.W + (size_t)(nn0 + row) * g.K + kt * 64 + c * 8),
;                                          (__attribute__((address_space(3))) unsigned*)(lb + 256 * 128 + seg * 1024 + lane * 16), 16, 0, 0);
;       }
;     };
; template <int MODE, int EPI, int BN>
; DI void gemm_phase(CP p, const GArgs& g, int NT, char* smem) {
;     ...
;   for (int e = j; e < total; e += nj) {
;     const int grp = e / (8 * NT);
;     const int rem = e - grp * 8 * NT;
;     const int e2 = e + nj;
;     const bool has_next = can_chain && e2 < total;
;     const int grp2 = e2 / (8 * NT), rem2 = e2 - grp2 * 8 * NT;
;     const int chain = can_chain ? ((first ? 0 : 1) | (has_next ? 2 : 0)) : 0;
;     gemm_tile<MODE, EPI, BN>(p, g, x + 8 * (grp * 8 + (rem & 7)), rem >> 3, smem, chain, x + 8 * (grp2 * 8 + (rem2 & 7)), rem2 >> 3);
.Lgemm_exit_1371:
	v_mfma_f32_32x32x16_bf16 v[114:129], v[224:227], v[232:235], v[114:129]
	v_mfma_f32_32x32x16_bf16 v[98:113], v[228:231], v[232:235], v[98:113]
	v_mfma_f32_32x32x16_bf16 v[82:97], v[224:227], v[240:243], v[82:97]
	v_mfma_f32_32x32x16_bf16 v[66:81], v[228:231], v[240:243], v[66:81]
	v_mfma_f32_32x32x16_bf16 v[50:65], v[224:227], v[244:247], v[50:65]
	v_mfma_f32_32x32x16_bf16 v[34:49], v[228:231], v[244:247], v[34:49]
	v_mfma_f32_32x32x16_bf16 v[18:33], v[224:227], v[248:251], v[18:33]
	v_mfma_f32_32x32x16_bf16 v[2:17], v[228:231], v[248:251], v[2:17]
	s_add_i32 s51, s51, s50
	s_cmpk_gt_u32 s51, 0x15f
	s_cselect_b64 s[10:11], -1, 0
	s_and_b64 vcc, exec, s[10:11]
	s_cbranch_vccnz .LBB0_1374
	s_mul_hi_u32 s16, s51, 0xba2e8ba3
	s_lshr_b32 s16, s16, 7
	s_mul_i32 s17, s16, 0xffffff50
	s_lshl_b32 s43, s51, 3
	s_add_i32 s17, s17, s51
	s_lshl_b32 s16, s16, 6
	s_and_b32 s43, s43, 56
	s_or_b32 s16, s16, s43
	s_lshl_b32 s17, s17, 5
	s_or_b32 s16, s16, s72
	s_and_b32 s17, s17, 0xffffff00
	s_lshl_b32 s16, s16, 8
	v_add_u32_e32 v148, s17, v158
	v_add_u32_e32 v138, s16, v156
	v_ashrrev_i32_e32 v149, 31, v148
	v_ashrrev_i32_e32 v139, 31, v138
	v_lshl_add_u64 v[176:177], s[46:47], 0, v[136:137]
	v_lshl_add_u64 v[136:137], s[48:49], 0, v[136:137]
	v_lshlrev_b64 v[148:149], 11, v[148:149]
	v_add3_u32 v0, 0, v167, v168
	v_add_u32_e32 v140, s16, v158
	v_add_u32_e32 v142, s16, v164
	v_add_u32_e32 v144, s16, v166
	v_lshlrev_b64 v[138:139], 11, v[138:139]
	v_lshl_add_u64 v[136:137], v[136:137], 0, v[148:149]
	v_lshl_add_u64 v[148:149], s[48:49], 0, v[134:135]
	v_lshl_add_u64 v[134:135], s[46:47], 0, v[134:135]
	v_readfirstlane_b32 s16, v0
	v_lshl_add_u64 v[134:135], v[134:135], 0, v[138:139]
	s_mov_b32 m0, s16
	v_ashrrev_i32_e32 v141, 31, v140
	global_load_lds_dwordx4 v[134:135], off
	v_add3_u32 v134, 0, v157, v168
	v_ashrrev_i32_e32 v143, 31, v142
	v_lshlrev_b64 v[140:141], 11, v[140:141]
	v_readfirstlane_b32 s16, v134
	v_add3_u32 v135, 0, v159, v168
	v_lshlrev_b64 v[142:143], 11, v[142:143]
	v_lshl_add_u64 v[202:203], s[48:49], 0, v[132:133]
	v_lshl_add_u64 v[132:133], s[46:47], 0, v[132:133]
	v_lshl_add_u64 v[140:141], v[176:177], 0, v[140:141]
	s_mov_b32 m0, s16
	v_readfirstlane_b32 s16, v135
	v_lshl_add_u64 v[132:133], v[132:133], 0, v[142:143]
	global_load_lds_dwordx4 v[140:141], off
	s_mov_b32 m0, s16
	v_ashrrev_i32_e32 v145, 31, v144
	v_add_u32_e32 v146, s17, v156
	global_load_lds_dwordx4 v[132:133], off
	v_add3_u32 v132, 0, v165, v168
	v_ashrrev_i32_e32 v147, 31, v146
	v_lshl_add_u64 v[200:201], s[46:47], 0, v[130:131]
	v_lshlrev_b64 v[144:145], 11, v[144:145]
	v_readfirstlane_b32 s16, v132
	v_add_u32_e32 v0, 0x8000, v0
	v_add_u32_e32 v150, s17, v164
	v_add_u32_e32 v152, s17, v166
	v_lshlrev_b64 v[146:147], 11, v[146:147]
	v_lshl_add_u64 v[144:145], v[200:201], 0, v[144:145]
	s_mov_b32 m0, s16
	v_readfirstlane_b32 s16, v0
	v_add_u32_e32 v0, 0x8000, v134
	v_ashrrev_i32_e32 v151, 31, v150
	v_ashrrev_i32_e32 v153, 31, v152
	v_lshl_add_u64 v[146:147], v[148:149], 0, v[146:147]
	global_load_lds_dwordx4 v[144:145], off
	s_mov_b32 m0, s16
	v_readfirstlane_b32 s16, v0
	v_add_u32_e32 v0, 0x8000, v135
	v_lshlrev_b64 v[150:151], 11, v[150:151]
	v_lshlrev_b64 v[152:153], 11, v[152:153]
	global_load_lds_dwordx4 v[146:147], off
	s_mov_b32 m0, s16
	v_readfirstlane_b32 s16, v0
	v_add_u32_e32 v0, 0x8000, v132
	v_lshl_add_u64 v[152:153], s[48:49], 0, v[152:153]
	v_lshl_add_u64 v[150:151], v[202:203], 0, v[150:151]
	global_load_lds_dwordx4 v[136:137], off
	s_mov_b32 m0, s16
	v_readfirstlane_b32 s16, v0
	global_load_lds_dwordx4 v[150:151], off
	v_lshl_add_u64 v[130:131], v[152:153], 0, v[130:131]
	s_mov_b32 m0, s16
	s_nop 0
	global_load_lds_dwordx4 v[130:131], off

; #define LAS __attribute__((address_space(3)))
; template <bool COOP>
; __global__ void __launch_bounds__(NTHR) mega(Params pp, int lo, int hi) {
;   extern __shared__ __attribute__((aligned(16))) char smem[];
;   const __attribute__((address_space(4))) Params* kp = (const __attribute__((address_space(4))) Params*)__builtin_amdgcn_kernarg_segment_ptr();
;   volatile LAS unsigned* st = (volatile LAS unsigned*)(smem + SMEM_BYTES - 32);
	.amdhsa_kernel _Z4megaILb1EEv6Paramsii
		.amdhsa_group_segment_fixed_size 8192
		.amdhsa_private_segment_fixed_size 0
		.amdhsa_kernarg_size 616
		.amdhsa_user_sgpr_count 2
		.amdhsa_user_sgpr_dispatch_ptr 0
		.amdhsa_user_sgpr_queue_ptr 0
		.amdhsa_user_sgpr_kernarg_segment_ptr 1
		.amdhsa_user_sgpr_dispatch_id 0
		.amdhsa_user_sgpr_kernarg_preload_length 0
		.amdhsa_user_sgpr_kernarg_preload_offset 0
		.amdhsa_user_sgpr_private_segment_size 0
		.amdhsa_uses_dynamic_stack 0
		.amdhsa_enable_private_segment 0
		.amdhsa_system_sgpr_workgroup_id_x 1
		.amdhsa_system_sgpr_workgroup_id_y 0
		.amdhsa_system_sgpr_workgroup_id_z 0
		.amdhsa_system_sgpr_workgroup_info 0
		.amdhsa_system_vgpr_workitem_id 2
		.amdhsa_next_free_vgpr 256
		.amdhsa_next_free_sgpr 100
		.amdhsa_accum_offset 256
		.amdhsa_reserve_vcc 1
		.amdhsa_float_round_mode_32 0
		.amdhsa_float_round_mode_16_64 0
		.amdhsa_float_denorm_mode_32 3
		.amdhsa_float_denorm_mode_16_64 3
		.amdhsa_dx10_clamp 1
		.amdhsa_ieee_mode 1
		.amdhsa_fp16_overflow 0
		.amdhsa_tg_split 0
		.amdhsa_exception_fp_ieee_invalid_op 0
		.amdhsa_exception_fp_denorm_src 0
		.amdhsa_exception_fp_ieee_div_zero 0
		.amdhsa_exception_fp_ieee_overflow 0
		.amdhsa_exception_fp_ieee_underflow 0
		.amdhsa_exception_fp_ieee_inexact 0
		.amdhsa_exception_int_div_zero 0
	.end_amdhsa_kernel

; #define LAS __attribute__((address_space(3)))
; template <bool COOP>
; __global__ void __launch_bounds__(NTHR) mega(Params pp, int lo, int hi) {
;   extern __shared__ __attribute__((aligned(16))) char smem[];
;   const __attribute__((address_space(4))) Params* kp = (const __attribute__((address_space(4))) Params*)__builtin_amdgcn_kernarg_segment_ptr();
;   volatile LAS unsigned* st = (volatile LAS unsigned*)(smem + SMEM_BYTES - 32);
amdhsa.kernels:
  - .agpr_count:     0
    .args:
      - .offset:         0
        .size:           352
        .value_kind:     by_value
      - .offset:         352
        .size:           4
        .value_kind:     by_value
      - .offset:         356
        .size:           4
        .value_kind:     by_value
      - .offset:         360
        .size:           4
        .value_kind:     hidden_block_count_x
      - .offset:         364
        .size:           4
        .value_kind:     hidden_block_count_y
      - .offset:         368
        .size:           4
        .value_kind:     hidden_block_count_z
      - .offset:         372
        .size:           2
        .value_kind:     hidden_group_size_x
      - .offset:         374
        .size:           2
        .value_kind:     hidden_group_size_y
      - .offset:         376
        .size:           2
        .value_kind:     hidden_group_size_z
      - .offset:         378
        .size:           2
        .value_kind:     hidden_remainder_x
      - .offset:         380
        .size:           2
        .value_kind:     hidden_remainder_y
      - .offset:         382
        .size:           2
        .value_kind:     hidden_remainder_z
      - .offset:         400
        .size:           8
        .value_kind:     hidden_global_offset_x
      - .offset:         408
        .size:           8
        .value_kind:     hidden_global_offset_y
      - .offset:         416
        .size:           8
        .value_kind:     hidden_global_offset_z
      - .offset:         424
        .size:           2
        .value_kind:     hidden_grid_dims
      - .offset:         448
        .size:           8
        .value_kind:     hidden_multigrid_sync_arg
      - .offset:         480
        .size:           4
        .value_kind:     hidden_dynamic_lds_size
    .group_segment_fixed_size: 8192
    .kernarg_segment_align: 8
    .kernarg_segment_size: 616
    .language:       OpenCL C
    .language_version:
      - 2
      - 0
    .max_flat_workgroup_size: 512
    .name:           _Z4megaILb1EEv6Paramsii
    .private_segment_fixed_size: 0
    .sgpr_count:     106
    .sgpr_spill_count: 137
    .symbol:         _Z4megaILb1EEv6Paramsii.kd
    .uniform_work_group_size: 1
    .uses_dynamic_stack: false
    .vgpr_count:     256
    .vgpr_spill_count: 0
    .wavefront_size: 64
